# NA blocks: second group of four guarded QK fragment-read pairs also issued up front into spare quads
# baseline (speedup 1.0000x reference)
.LBB0_1408:
	ds_read_b128 v[132:135], v118 offset:9216
	ds_read_b128 v[136:139], v118 offset:9280
	ds_read_b128 v[140:143], v96 offset:11520
	ds_read_b128 v[144:147], v96 offset:11584
	ds_read_b128 v[148:151], v96 offset:13824
	ds_read_b128 v[152:155], v96 offset:13888
	ds_read_b128 v[156:159], v96 offset:16128
	ds_read_b128 v[160:163], v96 offset:16192
	v_mov_b32_e32 v76, 0
	s_and_b64 vcc, exec, s[18:19]
	v_mov_b32_e32 v72, 0
	v_mov_b32_e32 v73, 0
	v_mov_b32_e32 v74, 0
	v_mov_b32_e32 v75, 0
	s_cbranch_vccnz .LBB0_1410
	s_waitcnt lgkmcnt(6)
	v_mfma_f32_16x16x32_bf16 v[60:63], v[132:135], v[0:3], 0
	s_nop 0
	v_mfma_f32_16x16x32_bf16 v[72:75], v[136:139], v[8:11], v[60:63]
.LBB0_1410:
	s_and_b64 vcc, exec, s[22:23]
	v_mov_b32_e32 v77, 0
	v_mov_b32_e32 v78, 0
	v_mov_b32_e32 v79, 0
	s_cbranch_vccnz .LBB0_1412
	s_nop 0
	s_waitcnt lgkmcnt(4)
	v_mfma_f32_16x16x32_bf16 v[60:63], v[140:143], v[0:3], 0
	s_nop 0
	v_mfma_f32_16x16x32_bf16 v[76:79], v[144:147], v[8:11], v[60:63]
.LBB0_1412:
	s_nop 5
	v_mov_b32_e32 v60, 0
	s_and_b64 vcc, exec, s[24:25]
	v_mov_b32_e32 v68, 0
	v_mov_b32_e32 v69, 0
	v_mov_b32_e32 v70, 0
	v_mov_b32_e32 v71, 0
	s_cbranch_vccnz .LBB0_1414
	s_waitcnt lgkmcnt(2)
	v_mfma_f32_16x16x32_bf16 v[62:65], v[148:151], v[0:3], 0
	s_nop 0
	v_mfma_f32_16x16x32_bf16 v[68:71], v[152:155], v[8:11], v[62:65]
.LBB0_1414:
	s_and_b64 vcc, exec, s[26:27]
	v_mov_b32_e32 v61, 0
	s_nop 3
	v_mov_b32_e32 v62, 0
	v_mov_b32_e32 v63, 0
	s_cbranch_vccnz .LBB0_1416
	s_waitcnt lgkmcnt(0)
	v_mfma_f32_16x16x32_bf16 v[60:63], v[156:159], v[0:3], 0
	s_nop 0
	v_mfma_f32_16x16x32_bf16 v[60:63], v[160:163], v[8:11], v[60:63]
.LBB0_1416:
	s_waitcnt lgkmcnt(0)
	s_and_b64 vcc, exec, s[20:21]
	s_cbranch_vccnz .LBB0_1458
	v_mov_b32_e32 v67, 0xf149f2ca
	s_and_b64 vcc, exec, s[18:19]
	v_mov_b32_e32 v66, 0xf149f2ca
	v_mov_b32_e32 v65, 0xf149f2ca
	v_mov_b32_e32 v64, 0xf149f2ca
	s_cbranch_vccnz .LBB0_1427
	v_mov_b32_e32 v65, 0xf149f2ca
	v_mov_b32_e32 v64, 0xf149f2ca
	v_mov_b32_e32 v67, 0xf149f2ca
	v_mov_b32_e32 v66, 0xf149f2ca
	v_add_u32_e32 v132, s72, v113
	ds_read_b32 v132, v132 offset:37856
	v_add_u32_e32 v133, s72, v112
	ds_read_b32 v133, v133 offset:37856
	v_add_u32_e32 v134, s72, v111
	ds_read_b32 v134, v134 offset:37856
	v_add_u32_e32 v135, s72, v110
	ds_read_b32 v135, v135 offset:37856
	s_waitcnt lgkmcnt(0)
	v_add_f32_e32 v132, v72, v132
	v_cndmask_b32_e64 v64, v64, v132, s[0:1]
	v_add_f32_e32 v133, v73, v133
	v_cndmask_b32_e64 v65, v65, v133, s[4:5]
	v_add_f32_e32 v134, v74, v134
	v_cndmask_b32_e64 v66, v66, v134, s[6:7]
	v_add_f32_e32 v135, v75, v135
	v_cndmask_b32_e64 v67, v67, v135, s[8:9]
